# v28
# baseline (speedup 1.0000x reference)
.LBB0_63:
	s_sleep 28
	global_load_dword v2, v0, s[6:7] offset:32 sc1
	s_waitcnt vmcnt(0)
	v_and_b32_e32 v2, 0xffff0000, v2
	v_cmp_ne_u32_e32 vcc, v2, v1
	s_or_b64 s[8:9], vcc, s[8:9]
	s_andn2_b64 exec, exec, s[8:9]
	s_cbranch_execnz .LBB0_63

.LBB0_266:
	s_sleep 28
	global_load_dword v2, v0, s[6:7] offset:32 sc1
	s_waitcnt vmcnt(0)
	v_and_b32_e32 v2, 0xffff0000, v2
	v_cmp_ne_u32_e32 vcc, v2, v1
	s_or_b64 s[10:11], vcc, s[10:11]
	s_andn2_b64 exec, exec, s[10:11]
	s_cbranch_execnz .LBB0_266

.LBB0_379:
	s_sleep 28
	global_load_dword v2, v0, s[0:1] offset:32 sc1
	s_waitcnt vmcnt(0)
	v_and_b32_e32 v2, 0xffff0000, v2
	v_cmp_ne_u32_e32 vcc, v2, v1
	s_or_b64 s[4:5], vcc, s[4:5]
	s_andn2_b64 exec, exec, s[4:5]
	s_cbranch_execnz .LBB0_379
